# speedup vs baseline: 1.0808x; 1.0020x over previous
;   __device__ __forceinline__ const float* in(int i) const { return reinterpret_cast<const float*>(ld64(i * 8)); }
;   __device__ __forceinline__ float* out() const { return reinterpret_cast<float*>(ld64(26 * 8)); }
;   __device__ __forceinline__ unsigned char* ws() const { return reinterpret_cast<unsigned char*>(ld64(27 * 8)); }
; __device__ __forceinline__ int opaque_tid() { int t = threadIdx.x; asm volatile("" : "+v"(t)); return t; }
; template <int MODE>
; __device__ __forceinline__ void phase_rows(const PRef& p, const float* __restrict__ vsrc, const float* __restrict__ g1, const float* __restrict__ g2, float coef, int nsplit) {
;   const int tidx = opaque_tid();
;   const int lane = tidx & 63, wave = tidx >> 6;
;   bf16* xn = (bf16*)(p.ws() + WS_XN);
;   float* hbuf = p.out() + O_Y;
;   const float* xp = p.in(0); const float* xs_ = p.in(1);
;   for (int row = blockIdx.x * 8 + wave; row < MT; row += gridDim.x * 8) {
;     float4 h[4];
;     if (MODE == 0) {
;       const float4* xs = reinterpret_cast<const float4*>(row < MP ? xp + (size_t)row * DM : xs_ + (size_t)(row - MP) * DM);
; #pragma unroll
;       for (int i = 0; i < 4; ++i) { const f32x4v t = __builtin_nontemporal_load(reinterpret_cast<const f32x4v*>(xs) + lane + 64 * i); h[i] = make_float4(t[0], t[1], t[2], t[3]); }
;     ...
;     for (int i = 0; i < 4; ++i) {
;       float4 g = reinterpret_cast<const float4*>(g2)[lane + 64 * i];
.LBB0_1166:
	s_add_i32 s0, 0, 0x23f30
	s_cmp_lg_u32 s0, -1
	s_cselect_b32 s0, s0, 0
	s_mov_b64 s[4:5], src_shared_base
	s_cselect_b32 s1, s5, 0
	v_mov_b32_e32 v2, s0
	s_add_i32 s0, 0, 0x23f34
	s_cmp_lg_u32 s0, -1
	v_mov_b32_e32 v3, s1
	s_cselect_b32 s0, s0, 0
	s_cselect_b32 s1, s5, 0
	flat_load_dword v0, v[2:3] sc0 sc1
	s_waitcnt vmcnt(0)
	v_mov_b32_e32 v2, s0
	v_mov_b32_e32 v3, s1
	flat_load_dword v2, v[2:3] sc0 sc1
	s_waitcnt vmcnt(0)
	v_readlane_b32 s0, v254, 5
	s_cmp_lg_u32 s0, -1
	s_cselect_b32 s0, s0, 0
	s_cselect_b32 s1, s5, 0
	v_mov_b32_e32 v3, s1
	s_waitcnt lgkmcnt(0)
	v_readfirstlane_b32 s8, v0
	v_mov_b32_e32 v0, v171
	v_readfirstlane_b32 s9, v2
	v_mov_b32_e32 v2, s0
	v_readlane_b32 s0, v254, 6
	s_cmp_lg_u32 s0, -1
	s_cselect_b32 s0, s0, 0
	s_cselect_b32 s1, s5, 0
	flat_load_dword v5, v[2:3] sc0 sc1
	s_waitcnt vmcnt(0)
	v_mov_b32_e32 v2, s0
	v_mov_b32_e32 v3, s1
	flat_load_dword v2, v[2:3] sc0 sc1
	s_waitcnt vmcnt(0)
	s_add_i32 s0, 0, 0x23fd0
	s_cmp_lg_u32 s0, -1
	s_cselect_b32 s0, s0, 0
	s_cselect_b32 s1, s5, 0
	v_mov_b32_e32 v3, s1
	v_ashrrev_i32_e32 v4, 6, v0
	s_waitcnt lgkmcnt(0)
	v_readfirstlane_b32 s10, v5
	v_readfirstlane_b32 s11, v2
	v_mov_b32_e32 v2, s0
	s_add_i32 s0, 0, 0x23fd4
	s_cmp_lg_u32 s0, -1
	flat_load_dword v2, v[2:3] sc0 sc1
	s_waitcnt vmcnt(0)
	s_cselect_b32 s0, s0, 0
	s_cselect_b32 s1, s5, 0
	s_waitcnt lgkmcnt(0)
	v_mov_b32_e32 v2, s0
	s_add_i32 s0, 0, 0x23f00
	v_mov_b32_e32 v3, s1
	s_cmp_lg_u32 s0, -1
	flat_load_dword v2, v[2:3] sc0 sc1
	s_waitcnt vmcnt(0)
	s_cselect_b32 s0, s0, 0
	s_cselect_b32 s1, s5, 0
	s_waitcnt lgkmcnt(0)
	v_mov_b32_e32 v2, s0
	s_add_i32 s0, 0, 0x23f04
	s_cmp_lg_u32 s0, -1
	v_mov_b32_e32 v3, s1
	s_cselect_b32 s0, s0, 0
	s_cselect_b32 s1, s5, 0
	flat_load_dword v5, v[2:3] sc0 sc1
	s_waitcnt vmcnt(0)
	v_mov_b32_e32 v2, s0
	v_mov_b32_e32 v3, s1
	flat_load_dword v2, v[2:3] sc0 sc1
	s_waitcnt vmcnt(0)
	s_add_i32 s4, 0, 0x23f08
	s_cmp_lg_u32 s4, -1
	s_cselect_b32 s4, s4, 0
	s_cselect_b32 s6, s5, 0
	v_mov_b32_e32 v3, s6
	v_readlane_b32 s6, v254, 42
	s_waitcnt lgkmcnt(0)
	v_readfirstlane_b32 s0, v5
	v_add_u32_e32 v10, s6, v4
	s_movk_i32 s6, 0x4100
	v_readfirstlane_b32 s1, v2
	v_mov_b32_e32 v2, s4
	s_add_i32 s4, 0, 0x23f0c
	s_cmp_lg_u32 s4, -1
	s_cselect_b32 s4, s4, 0
	s_cselect_b32 s5, s5, 0
	flat_load_dword v5, v[2:3] sc0 sc1
	s_waitcnt vmcnt(0)
	v_mov_b32_e32 v2, s4
	v_mov_b32_e32 v3, s5
	flat_load_dword v2, v[2:3] sc0 sc1
	s_waitcnt vmcnt(0)
	v_cmp_gt_i32_e32 vcc, s6, v10
	s_waitcnt lgkmcnt(0)
	v_readfirstlane_b32 s4, v5
	v_readfirstlane_b32 s5, v2
	s_and_saveexec_b64 s[6:7], vcc
	s_cbranch_execz .LBB0_1173
	v_and_b32_e32 v6, 63, v0
	v_lshlrev_b32_e32 v0, 4, v6
	v_lshl_add_u64 v[12:13], s[8:9], 0, v[0:1]
	flat_load_dwordx4 v[2:5], v[12:13]
	flat_load_dwordx4 v[228:231], v[12:13] offset:1024
	flat_load_dwordx4 v[232:235], v[12:13] offset:2048
	flat_load_dwordx4 v[236:239], v[12:13] offset:3072
	v_xor_b32_e32 v0, 32, v193
	v_cmp_lt_i32_e32 vcc, v0, v195
	s_mov_b64 s[8:9], 0x2a00000
	s_nop 0
	v_cndmask_b32_e32 v0, v193, v0, vcc
	v_cmp_lt_i32_e32 vcc, v253, v195
	v_lshlrev_b32_e32 v16, 2, v0
	s_nop 0
	v_cndmask_b32_e32 v0, v193, v253, vcc
	v_cmp_lt_i32_e32 vcc, v210, v195
	v_lshlrev_b32_e32 v17, 2, v0
	s_nop 0
	v_cndmask_b32_e32 v0, v193, v210, vcc
	v_lshlrev_b32_e32 v18, 2, v0
	v_xor_b32_e32 v0, 4, v193
	v_cmp_lt_i32_e32 vcc, v0, v195
	s_nop 1
	v_cndmask_b32_e32 v0, v193, v0, vcc
	v_lshlrev_b32_e32 v19, 2, v0
	v_xor_b32_e32 v0, 2, v193
	v_cmp_lt_i32_e32 vcc, v0, v195
	s_nop 1
	v_cndmask_b32_e32 v0, v193, v0, vcc
	v_lshlrev_b32_e32 v20, 2, v0
	v_xor_b32_e32 v0, 1, v193
	v_cmp_lt_i32_e32 vcc, v0, v195
	s_nop 1
	v_cndmask_b32_e32 v0, v193, v0, vcc
	v_lshlrev_b32_e32 v21, 2, v0
	v_lshlrev_b32_e32 v0, 3, v6
	v_lshl_add_u64 v[8:9], s[10:11], 0, v[0:1]
	v_lshl_add_u64 v[14:15], v[8:9], 0, s[8:9]
	s_mov_b64 s[8:9], 0
	v_lshlrev_b32_e32 v0, 4, v6
	s_movk_i32 s10, 0x3fff
	v_cmp_lt_i32_e32 vcc, s10, v10
	v_add_u32_e32 v57, 0xffffc000, v10
	v_mov_b32_e32 v59, 0
	v_mov_b32_e32 v60, s0
	v_cndmask_b32_e32 v58, v10, v57, vcc
	v_lshlrev_b64 v[58:59], 12, v[58:59]
	v_mov_b32_e32 v61, s1
	v_mov_b32_e32 v57, s4
	v_cndmask_b32_e32 v60, v60, v57, vcc
	v_mov_b32_e32 v57, s5
	v_cndmask_b32_e32 v61, v61, v57, vcc
	v_lshl_add_u64 v[58:59], v[60:61], 0, v[58:59]
	v_lshl_add_u64 v[58:59], v[58:59], 0, v[0:1]
	global_load_dwordx4 v[40:43], v[58:59], off nt
	global_load_dwordx4 v[44:47], v[58:59], off offset:1024 nt
	global_load_dwordx4 v[48:51], v[58:59], off offset:2048 nt
	global_load_dwordx4 v[52:55], v[58:59], off offset:3072 nt
; template <int MODE>
; __device__ __forceinline__ void phase_rows(const PRef& p, const float* __restrict__ vsrc, const float* __restrict__ g1, const float* __restrict__ g2, float coef, int nsplit) {
;     ...
;   for (int row = blockIdx.x * 8 + wave; row < MT; row += gridDim.x * 8) {
;     float4 h[4];
;     if (MODE == 0) {
;       const float4* xs = reinterpret_cast<const float4*>(row < MP ? xp + (size_t)row * DM : xs_ + (size_t)(row - MP) * DM);
; #pragma unroll
;       for (int i = 0; i < 4; ++i) { const f32x4v t = __builtin_nontemporal_load(reinterpret_cast<const f32x4v*>(xs) + lane + 64 * i); h[i] = make_float4(t[0], t[1], t[2], t[3]); }
;     ...
;     float ss2 = 0.f;
; #pragma unroll
;     for (int i = 0; i < 4; ++i) ss2 += h[i].x * h[i].x + h[i].y * h[i].y + h[i].z * h[i].z + h[i].w * h[i].w;
;     ss2 = wave_sum(ss2);
;     const float r2 = rsqrtf(ss2 * (1.f / DM) + RMS_EPS);
; #pragma unroll
;     for (int i = 0; i < 4; ++i) {
;       float4 g = reinterpret_cast<const float4*>(g2)[lane + 64 * i];
;       float o0 = h[i].x * r2 * g.x, o1 = h[i].y * r2 * g.y, o2 = h[i].z * r2 * g.z, o3 = h[i].w * r2 * g.w;
;       if (MODE == 3) {
;         __builtin_nontemporal_store(f32x4v{o0, o1, o2, o3}, reinterpret_cast<f32x4v*>(hbuf + (size_t)row * DM) + lane + 64 * i);
;       } else {
;         u32x2 w = {cvtpk(o0, o1), cvtpk(o2, o3)};
;         reinterpret_cast<u32x2*>(xn + (size_t)row * DM)[lane + 64 * i] = w;
;       }
;     }
.Lmy_r0_loop:
	s_waitcnt vmcnt(0)
	v_mov_b64_e32 v[22:23], v[40:41]
	v_mov_b64_e32 v[24:25], v[42:43]
	v_mov_b64_e32 v[26:27], v[44:45]
	v_mov_b64_e32 v[28:29], v[46:47]
	v_mov_b64_e32 v[30:31], v[48:49]
	v_mov_b64_e32 v[32:33], v[50:51]
	v_mov_b64_e32 v[6:7], v[52:53]
	v_mov_b64_e32 v[8:9], v[54:55]
	v_mov_b32_e32 v11, 0
	v_readlane_b32 s10, v254, 21
	v_add_u32_e32 v56, s10, v10
	s_movk_i32 s10, 0x4100
	v_cmp_gt_i32_e32 vcc, s10, v56
	s_cbranch_vccz .Lmy_r0_nopref
	s_movk_i32 s10, 0x3fff
	v_cmp_lt_i32_e32 vcc, s10, v56
	v_add_u32_e32 v57, 0xffffc000, v56
	v_mov_b32_e32 v59, 0
	v_mov_b32_e32 v60, s0
	v_cndmask_b32_e32 v58, v56, v57, vcc
	v_lshlrev_b64 v[58:59], 12, v[58:59]
	v_mov_b32_e32 v61, s1
	v_mov_b32_e32 v57, s4
	v_cndmask_b32_e32 v60, v60, v57, vcc
	v_mov_b32_e32 v57, s5
	v_cndmask_b32_e32 v61, v61, v57, vcc
	v_lshl_add_u64 v[58:59], v[60:61], 0, v[58:59]
	v_lshl_add_u64 v[58:59], v[58:59], 0, v[0:1]
	global_load_dwordx4 v[40:43], v[58:59], off nt
	global_load_dwordx4 v[44:47], v[58:59], off offset:1024 nt
	global_load_dwordx4 v[48:51], v[58:59], off offset:2048 nt
	global_load_dwordx4 v[52:55], v[58:59], off offset:3072 nt
.Lmy_r0_nopref:
	s_mov_b32 s10, 0x800000
	v_mov_b32_e32 v36, v23
	v_mov_b32_e32 v37, v27
	v_mov_b32_e32 v34, v22
	v_mov_b32_e32 v35, v26
	v_pk_mul_f32 v[36:37], v[36:37], v[36:37]
	v_mov_b32_e32 v38, v31
	v_pk_fma_f32 v[34:35], v[34:35], v[34:35], v[36:37]
	v_mov_b32_e32 v36, v24
	v_mov_b32_e32 v37, v28
	v_pk_fma_f32 v[34:35], v[36:37], v[36:37], v[34:35]
	v_mov_b32_e32 v36, v25
	v_mov_b32_e32 v37, v29
	v_mov_b32_e32 v39, v7
	v_pk_fma_f32 v[34:35], v[36:37], v[36:37], v[34:35]
	v_mov_b32_e32 v36, v30
	v_mov_b32_e32 v37, v6
	v_pk_mul_f32 v[38:39], v[38:39], v[38:39]
	v_add_f32_e32 v34, v34, v35
	v_pk_fma_f32 v[36:37], v[36:37], v[36:37], v[38:39]
	v_mov_b32_e32 v38, v32
	v_mov_b32_e32 v39, v8
	v_pk_fma_f32 v[36:37], v[38:39], v[38:39], v[36:37]
	v_mov_b32_e32 v38, v33
	v_mov_b32_e32 v39, v9
	v_pk_fma_f32 v[36:37], v[38:39], v[38:39], v[36:37]
	s_nop 0
	v_add_f32_e32 v34, v34, v36
	v_add_f32_e32 v34, v34, v37
	ds_bpermute_b32 v35, v16, v34
	s_waitcnt lgkmcnt(0)
	v_add_f32_e32 v34, v34, v35
	ds_bpermute_b32 v35, v17, v34
	s_waitcnt lgkmcnt(0)
	v_add_f32_e32 v34, v34, v35
	ds_bpermute_b32 v35, v18, v34
	s_waitcnt lgkmcnt(0)
	v_add_f32_e32 v34, v34, v35
	ds_bpermute_b32 v35, v19, v34
	s_waitcnt lgkmcnt(0)
	v_add_f32_e32 v34, v34, v35
	ds_bpermute_b32 v35, v20, v34
	s_waitcnt lgkmcnt(0)
	v_add_f32_e32 v34, v34, v35
	ds_bpermute_b32 v35, v21, v34
	s_waitcnt lgkmcnt(0)
	v_add_f32_e32 v34, v34, v35
	v_fmamk_f32 v34, v34, 0x3a800000, v190
	v_cmp_gt_f32_e32 vcc, s10, v34
	v_mul_f32_e32 v35, 0x4b800000, v34
	v_cndmask_b32_e32 v34, v34, v35, vcc
	v_rsq_f32_e32 v34, v34
	s_nop 0
	v_mul_f32_e32 v35, 0x45800000, v34
	v_cndmask_b32_e32 v36, v34, v35, vcc
	v_lshlrev_b64 v[34:35], 11, v[10:11]
	v_mul_f32_e32 v11, v22, v36
	v_mul_f32_e32 v22, v23, v36
	v_mul_f32_e32 v23, v24, v36
	v_mul_f32_e32 v22, v3, v22
	v_mul_f32_e32 v23, v4, v23
	v_mul_f32_e32 v24, v25, v36
	v_mul_f32_e32 v11, v2, v11
	v_mul_f32_e32 v24, v5, v24
	v_cvt_pk_bf16_f32 v22, v11, v22
	v_cvt_pk_bf16_f32 v23, v23, v24
	v_lshl_add_u64 v[34:35], v[14:15], 0, v[34:35]
	flat_store_dwordx2 v[34:35], v[22:23]
	v_mul_f32_e32 v11, v26, v36
	v_mul_f32_e32 v6, v6, v36
	v_mul_f32_e32 v7, v7, v36
	v_mul_f32_e32 v8, v8, v36
	v_mul_f32_e32 v9, v9, v36
	v_mul_f32_e32 v11, v228, v11
	v_mul_f32_e32 v22, v27, v36
	v_mul_f32_e32 v22, v229, v22
	v_mul_f32_e32 v23, v28, v36
	v_mul_f32_e32 v23, v230, v23
	v_mul_f32_e32 v24, v29, v36
	v_mul_f32_e32 v24, v231, v24
	v_cvt_pk_bf16_f32 v22, v11, v22
	v_cvt_pk_bf16_f32 v23, v23, v24
	flat_store_dwordx2 v[34:35], v[22:23] offset:512
	v_mul_f32_e32 v11, v30, v36
	v_mul_f32_e32 v11, v232, v11
	v_mul_f32_e32 v22, v31, v36
	v_mul_f32_e32 v22, v233, v22
	v_mul_f32_e32 v23, v32, v36
	v_mul_f32_e32 v23, v234, v23
	v_mul_f32_e32 v24, v33, v36
	v_mul_f32_e32 v24, v235, v24
	v_cvt_pk_bf16_f32 v22, v11, v22
	v_cvt_pk_bf16_f32 v23, v23, v24
	flat_store_dwordx2 v[34:35], v[22:23] offset:1024
	v_mul_f32_e32 v6, v6, v236
	v_mul_f32_e32 v7, v7, v237
	v_mul_f32_e32 v8, v8, v238
	v_mul_f32_e32 v9, v9, v239
	v_cvt_pk_bf16_f32 v6, v6, v7
	v_cvt_pk_bf16_f32 v7, v8, v9
	flat_store_dwordx2 v[34:35], v[6:7] offset:1536
	v_mov_b32_e32 v10, v56
	s_movk_i32 s10, 0x4100
	v_cmp_gt_i32_e32 vcc, s10, v10
	s_cbranch_vccnz .Lmy_r0_loop
